# attention main loop: K/V tile DMA sources as SGPR base + loop-invariant 32-bit lane offset (saddr form): the four 64-bit VALU pointer adds per two tiles become scalar adds; rescale-factor LDS address
# baseline (speedup 1.0000x reference)
; #define WAIT_BAR(N) asm volatile("s_waitcnt vmcnt(" #N ") lgkmcnt(0)\n\ts_barrier":::"memory")
;   #define DMA_K(t,slot) glds16(ksrc+(long)(t)*KVBLK*PD,(unsigned)__builtin_amdgcn_readfirstlane(kdst+(slot)))
;   #define DMA_V(t,slot) glds16(vsrc+(long)(t)*KVBLK*PD,(unsigned)__builtin_amdgcn_readfirstlane(vdst+(slot)))
;   #define CMASK(P0,P1,t) do{int jb_=(t)-(NT-4); if(jb_>=0)cmask(P0,P1,jb_,qrel,hi);}while(0)
;   #define START(P0,P1) do{ const float rm=rowmax(P0,P1); resc=false; \
;     { const float dl=rm; mhat=fadd_s(mhat,dl); \
;       _Pragma("unroll") for(int r=0;r<16;++r){P0[r]=fsub_s(P0[r],dl);P1[r]=fsub_s(P1[r],dl);} \
;       _Pragma("unroll") for(int r=0;r<16;++r)negm[r]=-mhat; asm volatile("":"+v"(negm)); } \
;     _Pragma("unroll") for(int r=0;r<16;++r)P0[r]=__builtin_amdgcn_exp2f(P0[r]); }while(0)
;   #define ROT() do{sl_prev=sl_cur;sl_cur=sl_next;sl_next=(sl_next==(NSLOT-1)*SLOTB)?0:sl_next+SLOTB;}while(0)
;   #define CMASK(P0,P1,t) do{}while(0)
;   #define CMASK(P0,P1,t) do{int jb_=(t)-(NT-4); if(jb_>=0)cmask(P0,P1,jb_,qrel,hi);}while(0)
; template<int THRL> __device__ __forceinline__ void attn_unit(int b,int h,int qb,const bf16*Q,const bf16*__restrict__ K,const bf16*__restrict__ V,bf16*O,char*shm,const int wid){
;     ...
;   f32x16 pA0,pA1,pB0,pB1;
;   int sl_prev=0,sl_cur=0,sl_next=SLOTB;
;     ...
;   DMA_K(2,2*SLOTB);
;   WAIT_BAR(3);
;   qkt(pA0,pA1,Kbase,qr,negm,r32,hi);asm volatile("s_nop 15\n\ts_nop 7":"+v"(pA0),"+v"(pA1));CMASK(pA0,pA1,0);
;   START(pA0,pA1);
;   _Pragma("unroll") for(int r=0;r<16;++r)pA1[r]=__builtin_amdgcn_exp2f(pA1[r]);
;   WAIT_BAR(0);
;   DMA_K(3,0);DMA_V(1,SLOTB);
;   ROT();
;   kload8(kf,kp0+sl_cur);
;   WAIT_BAR(2);
.LBB0_1545:
	v_lshlrev_b32_e32 v0, 1, v210
	v_and_b32_e32 v217, 32, v0
	v_lshlrev_b32_e32 v0, 4, v210
	v_and_b32_e32 v0, 0xc0, v0
	v_lshl_or_b32 v215, v213, 8, v0
	v_add_u32_e32 v0, 0, v217
	v_add3_u32 v221, v0, v214, v215
	v_max3_f32 v0, v18, v19, v2
	v_max3_f32 v36, v20, v21, v3
	s_sub_i32 s3, 0x1000, s36
	v_max3_f32 v0, v0, v4, v5
	v_max3_f32 v36, v36, v24, v25
	s_lshr_b32 s3, s3, 6
	v_max3_f32 v0, v0, v22, v23
	v_max3_f32 v36, v36, v8, v9
	s_cmp_lg_u32 0, -1
	v_max3_f32 v0, v0, v6, v7
	v_max3_f32 v36, v36, v28, v29
	v_lshl_add_u64 v[198:199], v[34:35], 0, s[22:23]
	v_max3_f32 v0, v0, v26, v27
	v_max3_f32 v36, v36, v12, v13
	s_mov_b32 s8, 1
	v_max3_f32 v0, v0, v10, v11
	v_max3_f32 v36, v36, v32, v33
	s_mov_b32 s38, 0
	v_max3_f32 v0, v0, v30, v31
	v_max3_f32 v36, v36, v16, v17
	v_lshlrev_b32_e32 v222, 4, v213
	v_max3_f32 v0, v0, v14, v15
	s_nop 0
	v_max_f32_e32 v0, v0, v36
	s_nop 0
	v_mov_b32_e32 v36, v0
	s_nop 1
	v_permlane32_swap_b32_e32 v0, v36
	v_max_f32_e32 v0, v0, v36
	s_nop 0
	v_add_f32_e32 v219, v1, v0
	v_sub_f32_e32 v2, v2, v0
	v_sub_f32_e32 v3, v3, v0
	v_sub_f32_e32 v18, v18, v0
	v_sub_f32_e32 v19, v19, v0
	v_sub_f32_e32 v20, v20, v0
	s_nop 0
	v_xor_b32_e32 v48, 0x80000000, v219
	v_mov_b32_e32 v49, v48
	v_mov_b32_e32 v50, v48
	v_mov_b32_e32 v51, v48
	v_mov_b32_e32 v52, v48
	v_mov_b32_e32 v53, v48
	v_mov_b32_e32 v54, v48
	v_mov_b32_e32 v55, v48
	v_mov_b32_e32 v56, v48
	v_mov_b32_e32 v57, v48
	v_mov_b32_e32 v58, v48
	v_mov_b32_e32 v59, v48
	v_mov_b32_e32 v60, v48
	v_mov_b32_e32 v61, v48
	v_mov_b32_e32 v62, v48
	v_mov_b32_e32 v63, v48
	s_waitcnt vmcnt(0) lgkmcnt(0)
	s_barrier
	v_exp_f32_e32 v64, v2
	v_exp_f32_e32 v65, v3
	v_lshl_add_u64 v[2:3], v[196:197], 0, s[20:21]
	s_mov_b32 s9, m0
	s_mov_b32 m0, s46
	s_nop 0
	global_load_lds_dwordx4 v[2:3], off
	s_mov_b32 m0, s9
	s_cselect_b32 s9, 0, 0
	s_add_i32 s9, s9, s45
	s_add_i32 s9, s9, 0x8000
	s_mov_b32 s13, m0
	s_mov_b32 m0, s9
	s_nop 0
	global_load_lds_dwordx4 v[198:199], off
	s_mov_b32 m0, s13
	ds_read_b128 v[188:191], v220 offset:8192
	ds_read_b128 v[184:187], v220 offset:8704
	ds_read_b128 v[180:183], v220 offset:10240
	ds_read_b128 v[176:179], v220 offset:10752
	ds_read_b128 v[172:175], v220 offset:12288
	ds_read_b128 v[168:171], v220 offset:12800
	ds_read_b128 v[164:167], v220 offset:14336
	ds_read_b128 v[160:163], v220 offset:14848
	v_sub_f32_e32 v4, v4, v0
	v_sub_f32_e32 v21, v21, v0
	v_sub_f32_e32 v5, v5, v0
	v_sub_f32_e32 v22, v22, v0
	v_sub_f32_e32 v6, v6, v0
	v_sub_f32_e32 v23, v23, v0
	v_sub_f32_e32 v7, v7, v0
	v_sub_f32_e32 v24, v24, v0
	v_sub_f32_e32 v8, v8, v0
	v_sub_f32_e32 v25, v25, v0
	v_sub_f32_e32 v9, v9, v0
	v_sub_f32_e32 v26, v26, v0
	v_sub_f32_e32 v10, v10, v0
	v_sub_f32_e32 v27, v27, v0
	v_sub_f32_e32 v11, v11, v0
	v_sub_f32_e32 v28, v28, v0
	v_sub_f32_e32 v12, v12, v0
	v_sub_f32_e32 v29, v29, v0
	v_sub_f32_e32 v13, v13, v0
	v_sub_f32_e32 v30, v30, v0
	v_sub_f32_e32 v14, v14, v0
	v_sub_f32_e32 v31, v31, v0
	v_sub_f32_e32 v15, v15, v0
	v_sub_f32_e32 v32, v32, v0
	v_sub_f32_e32 v16, v16, v0
	v_sub_f32_e32 v33, v33, v0
	v_sub_f32_e32 v0, v17, v0
	v_exp_f32_e32 v80, v18
	v_exp_f32_e32 v81, v19
	v_exp_f32_e32 v82, v20
	v_exp_f32_e32 v83, v21
	v_exp_f32_e32 v84, v22
	v_exp_f32_e32 v85, v23
	v_exp_f32_e32 v86, v24
	v_exp_f32_e32 v87, v25
	v_exp_f32_e32 v88, v26
	v_exp_f32_e32 v89, v27
	v_exp_f32_e32 v90, v28
	v_exp_f32_e32 v91, v29
	v_exp_f32_e32 v92, v30
	v_exp_f32_e32 v93, v31
	v_exp_f32_e32 v94, v32
	v_exp_f32_e32 v95, v33
	v_exp_f32_e32 v66, v4
	v_exp_f32_e32 v67, v5
	v_exp_f32_e32 v68, v6
	v_exp_f32_e32 v69, v7
	v_exp_f32_e32 v70, v8
	v_exp_f32_e32 v71, v9
	v_exp_f32_e32 v72, v10
	v_exp_f32_e32 v73, v11
	v_exp_f32_e32 v74, v12
	v_exp_f32_e32 v75, v13
	v_exp_f32_e32 v76, v14
	v_exp_f32_e32 v77, v15
	v_exp_f32_e32 v78, v16
	v_exp_f32_e32 v79, v0
	s_waitcnt vmcnt(2) lgkmcnt(0)
	s_barrier
	s_andn2_b64 vcc, exec, s[6:7]
	v_cmp_gt_u32_e64 s[6:7], 32, v210
	s_cbranch_vccnz .LBB0_1561
	v_mov_b32_e32 v14, v1
	v_mov_b32_e32 v15, v1
	v_lshl_add_u64 v[200:201], v[34:35], 0, s[20:21]
	v_mov_b32_e32 v0, v1
	v_mov_b32_e32 v2, v1
	v_mov_b32_e32 v3, v1
	v_mov_b32_e32 v4, v1
	v_mov_b32_e32 v5, v1
	v_mov_b32_e32 v6, v1
	v_mov_b32_e32 v7, v1
	v_mov_b32_e32 v8, v1
	v_mov_b32_e32 v9, v1
	v_mov_b32_e32 v10, v1
	v_mov_b32_e32 v11, v1
	v_mov_b32_e32 v12, v1
	v_mov_b32_e32 v13, v1
	v_mov_b64_e32 v[46:47], v[14:15]
	v_mov_b64_e32 v[30:31], v[14:15]
	v_lshl_add_u32 v204, v212, 2, s48
	v_lshl_add_u64 v[202:203], v[196:197], 0, s[24:25]
	s_mov_b32 s8, 0
	s_movk_i32 s38, 0x4000
	s_movk_i32 s40, 0x2000
	v_mov_b32_e32 v223, 0
	s_mov_b32 s39, 6
	v_readfirstlane_b32 s88, v202
	v_readfirstlane_b32 s89, v203
	v_readfirstlane_b32 s90, v200
	v_readfirstlane_b32 s91, v201
	v_add_u32_e32 v226, s48, v222
	s_nop 3
	v_subrev_u32_e32 v224, s88, v202
	v_subrev_u32_e32 v225, s90, v200
	v_mov_b64_e32 v[44:45], v[12:13]
	v_mov_b64_e32 v[42:43], v[10:11]
	v_mov_b64_e32 v[40:41], v[8:9]
	v_mov_b64_e32 v[38:39], v[6:7]
	v_mov_b64_e32 v[36:37], v[4:5]
	v_mov_b64_e32 v[34:35], v[2:3]
	v_mov_b64_e32 v[32:33], v[0:1]
	v_mov_b64_e32 v[28:29], v[12:13]
	v_mov_b64_e32 v[26:27], v[10:11]
	v_mov_b64_e32 v[24:25], v[8:9]
	v_mov_b64_e32 v[22:23], v[6:7]
	v_mov_b64_e32 v[20:21], v[4:5]
	v_mov_b64_e32 v[18:19], v[2:3]
	v_mov_b64_e32 v[16:17], v[0:1]
.LBB0_1547:
	v_add_u32_e32 v0, s8, v221
	ds_read_b64_tr_b16 v[192:193], v0 offset:24576
	ds_read_b64_tr_b16 v[194:195], v0 offset:25088
	s_waitcnt lgkmcnt(9)
	v_mfma_f32_32x32x16_bf16 v[112:127], v[188:191], v[148:151], v[48:63]
	v_add_f32_e32 v2, v80, v81
	v_add_f32_e32 v2, v82, v2
	v_add_f32_e32 v2, v83, v2
	v_add_f32_e32 v2, v84, v2
	v_add_f32_e32 v2, v85, v2
	v_cvt_pk_bf16_f32 v156, v80, v81
	v_cvt_pk_bf16_f32 v157, v82, v83
	ds_read_b64_tr_b16 v[188:189], v0 offset:28672
	ds_read_b64_tr_b16 v[190:191], v0 offset:29184
	s_waitcnt lgkmcnt(10)
	v_mfma_f32_32x32x16_bf16 v[96:111], v[184:187], v[148:151], v[48:63]
	v_add_f32_e32 v2, v86, v2
	v_add_f32_e32 v2, v87, v2
	v_add_f32_e32 v2, v88, v2
	v_add_f32_e32 v2, v89, v2
	v_cvt_pk_bf16_f32 v158, v84, v85
	v_cvt_pk_bf16_f32 v159, v86, v87
	ds_read_b64_tr_b16 v[184:185], v0 offset:25600
	ds_read_b64_tr_b16 v[186:187], v0 offset:26112
	s_waitcnt lgkmcnt(11)
	v_mfma_f32_32x32x16_bf16 v[112:127], v[180:183], v[140:143], v[112:127]
	v_add_f32_e32 v2, v90, v2
	v_add_f32_e32 v2, v91, v2
	v_add_f32_e32 v2, v92, v2
	v_add_f32_e32 v2, v93, v2
	v_cvt_pk_bf16_f32 v152, v88, v89
	v_cvt_pk_bf16_f32 v153, v90, v91
	ds_read_b64_tr_b16 v[84:85], v0 offset:29696
	ds_read_b64_tr_b16 v[86:87], v0 offset:30208
	s_waitcnt lgkmcnt(12)
	v_mfma_f32_32x32x16_bf16 v[96:111], v[176:179], v[140:143], v[96:111]
	v_add_f32_e32 v2, v94, v2
	v_add_f32_e32 v2, v95, v2
	v_add_f32_e32 v2, v64, v2
	v_add_f32_e32 v2, v65, v2
	v_cvt_pk_bf16_f32 v154, v92, v93
	v_cvt_pk_bf16_f32 v155, v94, v95
	ds_read_b64_tr_b16 v[80:81], v0 offset:26624
	ds_read_b64_tr_b16 v[82:83], v0 offset:27136
	s_waitcnt lgkmcnt(13)
	v_mfma_f32_32x32x16_bf16 v[112:127], v[172:175], v[132:135], v[112:127]
	v_add_f32_e32 v2, v66, v2
	v_add_f32_e32 v2, v67, v2
	v_add_f32_e32 v2, v68, v2
	v_add_f32_e32 v2, v69, v2
	v_cvt_pk_bf16_f32 v144, v64, v65
	v_cvt_pk_bf16_f32 v145, v66, v67
	ds_read_b64_tr_b16 v[10:11], v0 offset:30720
	ds_read_b64_tr_b16 v[12:13], v0 offset:31232
	s_waitcnt lgkmcnt(14)
	v_mfma_f32_32x32x16_bf16 v[96:111], v[168:171], v[132:135], v[96:111]
	v_add_f32_e32 v2, v70, v2
	v_add_f32_e32 v2, v71, v2
	v_add_f32_e32 v2, v72, v2
	v_add_f32_e32 v2, v73, v2
	v_cvt_pk_bf16_f32 v146, v68, v69
	v_cvt_pk_bf16_f32 v147, v70, v71
	ds_read_b64_tr_b16 v[6:7], v0 offset:27648
	ds_read_b64_tr_b16 v[8:9], v0 offset:28160
	s_waitcnt lgkmcnt(14)
	v_mfma_f32_32x32x16_bf16 v[112:127], v[164:167], v[128:131], v[112:127]
	v_add_f32_e32 v2, v74, v2
	v_add_f32_e32 v2, v75, v2
	v_add_f32_e32 v2, v76, v2
	v_add_f32_e32 v14, v77, v2
	v_cvt_pk_bf16_f32 v136, v72, v73
	v_cvt_pk_bf16_f32 v137, v74, v75
	ds_read_b64_tr_b16 v[2:3], v0 offset:31744
	ds_read_b64_tr_b16 v[4:5], v0 offset:32256
	v_mfma_f32_32x32x16_bf16 v[96:111], v[160:163], v[128:131], v[96:111]
	v_add_f32_e32 v0, v78, v14
	v_add_f32_e32 v0, v79, v0
	v_cvt_pk_bf16_f32 v138, v76, v77
	v_cvt_pk_bf16_f32 v139, v78, v79
	s_add_u32 s94, s88, s26
	s_addc_u32 s95, s89, s27
	s_add_i32 s8, s40, s46
	s_mov_b32 s9, m0
	s_mov_b32 m0, s8
	s_add_u32 s96, s90, s26
	s_addc_u32 s97, s91, s27
	global_load_lds_dwordx4 v224, s[94:95]
	s_add_i32 s8, s38, s47
	s_mov_b32 m0, s8
	s_nop 0
	global_load_lds_dwordx4 v225, s[96:97]
	s_mov_b32 m0, s9
	v_max3_f32 v14, v112, v113, v114
	v_max3_f32 v15, v115, v116, v117
	v_max3_f32 v14, v14, v118, v119
	v_max3_f32 v15, v15, v120, v121
	v_max3_f32 v14, v14, v122, v123
	v_max3_f32 v15, v15, v124, v125
	v_max3_f32 v14, v14, v126, v127
	v_max3_f32 v15, v15, v96, v97
	v_max3_f32 v14, v14, v98, v99
	v_max3_f32 v15, v15, v100, v101
	v_max3_f32 v14, v14, v102, v103
	v_max3_f32 v15, v15, v104, v105
	v_max3_f32 v14, v14, v106, v107
	v_max3_f32 v15, v15, v108, v109
	v_max3_f32 v64, v14, v110, v111
	v_add_f32_e32 v14, v223, v0
	v_max_f32_e32 v0, v64, v15
	v_mov_b32_e32 v15, v0
	s_nop 1
	v_permlane32_swap_b32_e32 v0, v15
	v_max_f32_e32 v0, v0, v15
	v_cmp_lt_f32_e32 vcc, s53, v0
	s_cmp_lg_u64 vcc, 0
	s_cselect_b64 s[8:9], -1, 0
	s_cbranch_vccnz .LBB0_1555
.LBB0_1548:
	s_waitcnt lgkmcnt(14)
	v_mfma_f32_32x32x16_bf16 v[32:47], v[156:159], v[192:195], v[32:47]
	v_exp_f32_e32 v112, v112
	v_exp_f32_e32 v113, v113
	v_exp_f32_e32 v114, v114
	v_exp_f32_e32 v115, v115
	s_waitcnt lgkmcnt(12)
	v_mfma_f32_32x32x16_bf16 v[16:31], v[156:159], v[188:191], v[16:31]
	v_exp_f32_e32 v116, v116
	v_exp_f32_e32 v117, v117
	v_exp_f32_e32 v118, v118
	v_exp_f32_e32 v119, v119
	v_add_u32_e32 v0, s38, v220
	ds_read_b128 v[64:67], v0
	ds_read_b128 v[160:163], v0 offset:512
	s_waitcnt lgkmcnt(12)
	v_mfma_f32_32x32x16_bf16 v[32:47], v[152:155], v[184:187], v[32:47]
	v_exp_f32_e32 v120, v120
	v_exp_f32_e32 v121, v121
	v_exp_f32_e32 v122, v122
	v_exp_f32_e32 v123, v123
	ds_read_b128 v[192:195], v0 offset:2048
	ds_read_b128 v[184:187], v0 offset:2560
	s_waitcnt lgkmcnt(12)
	v_mfma_f32_32x32x16_bf16 v[16:31], v[152:155], v[84:87], v[16:31]
	v_exp_f32_e32 v124, v124
	v_exp_f32_e32 v125, v125
	v_exp_f32_e32 v126, v126
	v_exp_f32_e32 v127, v127
	ds_read_b128 v[188:191], v0 offset:4096
	ds_read_b128 v[176:179], v0 offset:4608
	s_waitcnt lgkmcnt(12)
	v_mfma_f32_32x32x16_bf16 v[32:47], v[144:147], v[80:83], v[32:47]
	v_exp_f32_e32 v96, v96
	v_exp_f32_e32 v97, v97
	v_exp_f32_e32 v98, v98
	v_exp_f32_e32 v99, v99
	ds_read_b128 v[180:183], v0 offset:6144
	ds_read_b128 v[172:175], v0 offset:6656
	s_waitcnt lgkmcnt(12)
	v_mfma_f32_32x32x16_bf16 v[16:31], v[144:147], v[10:13], v[16:31]
	v_exp_f32_e32 v100, v100
	v_exp_f32_e32 v101, v101
	v_exp_f32_e32 v102, v102
	v_exp_f32_e32 v103, v103
	s_waitcnt lgkmcnt(10)
	v_mfma_f32_32x32x16_bf16 v[32:47], v[136:139], v[6:9], v[32:47]
	v_exp_f32_e32 v104, v104
	v_exp_f32_e32 v105, v105
	v_exp_f32_e32 v106, v106
	v_exp_f32_e32 v107, v107
	s_waitcnt lgkmcnt(8)
	v_mfma_f32_32x32x16_bf16 v[16:31], v[136:139], v[2:5], v[16:31]
	v_exp_f32_e32 v108, v108
	v_exp_f32_e32 v109, v109
	v_exp_f32_e32 v110, v110
	v_exp_f32_e32 v111, v111
	s_waitcnt vmcnt(2) lgkmcnt(0)
	s_barrier
	s_andn2_b64 vcc, exec, s[8:9]
	s_cbranch_vccnz .LBB0_1550
	s_waitcnt lgkmcnt(0)
	ds_read_b128 v[2:5], v226 offset:49248
	ds_read_b128 v[6:9], v226 offset:49216
	ds_read_b128 v[10:13], v226 offset:49184
	ds_read_b128 v[68:71], v226 offset:49152
	s_waitcnt lgkmcnt(3)
	v_pk_mul_f32 v[44:45], v[44:45], v[2:3]
	s_waitcnt lgkmcnt(2)
	v_pk_mul_f32 v[40:41], v[40:41], v[6:7]
	s_waitcnt lgkmcnt(1)
	v_pk_mul_f32 v[36:37], v[36:37], v[10:11]
	v_pk_mul_f32 v[46:47], v[46:47], v[4:5]
	v_pk_mul_f32 v[42:43], v[42:43], v[8:9]
	v_pk_mul_f32 v[38:39], v[38:39], v[12:13]
	s_waitcnt lgkmcnt(0)
	v_pk_mul_f32 v[34:35], v[34:35], v[70:71]
	v_pk_mul_f32 v[32:33], v[32:33], v[68:69]
	v_pk_mul_f32 v[28:29], v[28:29], v[2:3]
	v_pk_mul_f32 v[24:25], v[24:25], v[6:7]
	v_pk_mul_f32 v[20:21], v[20:21], v[10:11]
	v_pk_mul_f32 v[30:31], v[30:31], v[4:5]
	v_pk_mul_f32 v[26:27], v[26:27], v[8:9]
	v_pk_mul_f32 v[22:23], v[22:23], v[12:13]
	v_pk_mul_f32 v[18:19], v[18:19], v[70:71]
	v_pk_mul_f32 v[16:17], v[16:17], v[68:69]
.LBB0_1550:
	s_add_i32 s8, s38, 0x2000
	s_cmpk_lg_i32 s38, 0x4000
	s_cselect_b32 s13, s8, 0
	v_add_u32_e32 v4, s40, v221
	ds_read_b64_tr_b16 v[168:169], v4 offset:24576
	ds_read_b64_tr_b16 v[170:171], v4 offset:25088
	s_waitcnt lgkmcnt(9)
	v_mfma_f32_32x32x16_bf16 v[80:95], v[64:67], v[148:151], v[48:63]
	v_add_f32_e32 v2, v112, v113
	v_add_f32_e32 v2, v114, v2
	v_add_f32_e32 v2, v115, v2
	v_add_f32_e32 v2, v116, v2
	v_add_f32_e32 v2, v117, v2
	v_cvt_pk_bf16_f32 v156, v112, v113
	v_cvt_pk_bf16_f32 v157, v114, v115
	ds_read_b64_tr_b16 v[164:165], v4 offset:28672
	ds_read_b64_tr_b16 v[166:167], v4 offset:29184
	s_waitcnt lgkmcnt(10)
	v_mfma_f32_32x32x16_bf16 v[64:79], v[160:163], v[148:151], v[48:63]
	v_add_f32_e32 v2, v118, v2
	v_add_f32_e32 v2, v119, v2
	v_add_f32_e32 v2, v120, v2
	v_add_f32_e32 v2, v121, v2
	v_cvt_pk_bf16_f32 v158, v116, v117
	v_cvt_pk_bf16_f32 v159, v118, v119
	ds_read_b64_tr_b16 v[160:161], v4 offset:25600
	ds_read_b64_tr_b16 v[162:163], v4 offset:26112
	s_waitcnt lgkmcnt(11)
	v_mfma_f32_32x32x16_bf16 v[80:95], v[192:195], v[140:143], v[80:95]
	v_add_f32_e32 v2, v122, v2
	v_add_f32_e32 v2, v123, v2
	v_add_f32_e32 v2, v124, v2
	v_add_f32_e32 v2, v125, v2
	v_cvt_pk_bf16_f32 v152, v120, v121
	v_cvt_pk_bf16_f32 v153, v122, v123
	ds_read_b64_tr_b16 v[116:117], v4 offset:29696
	ds_read_b64_tr_b16 v[118:119], v4 offset:30208
	s_waitcnt lgkmcnt(12)
	v_mfma_f32_32x32x16_bf16 v[64:79], v[184:187], v[140:143], v[64:79]
	v_add_f32_e32 v2, v126, v2
	v_add_f32_e32 v2, v127, v2
	v_add_f32_e32 v2, v96, v2
	v_add_f32_e32 v2, v97, v2
	v_cvt_pk_bf16_f32 v154, v124, v125
	v_cvt_pk_bf16_f32 v155, v126, v127
	ds_read_b64_tr_b16 v[112:113], v4 offset:26624
	ds_read_b64_tr_b16 v[114:115], v4 offset:27136
	s_waitcnt lgkmcnt(13)
	v_mfma_f32_32x32x16_bf16 v[80:95], v[188:191], v[132:135], v[80:95]
	v_add_f32_e32 v2, v98, v2
	v_add_f32_e32 v2, v99, v2
	v_add_f32_e32 v2, v100, v2
	v_add_f32_e32 v2, v101, v2
	v_cvt_pk_bf16_f32 v144, v96, v97
	v_cvt_pk_bf16_f32 v145, v98, v99
	ds_read_b64_tr_b16 v[10:11], v4 offset:30720
	ds_read_b64_tr_b16 v[12:13], v4 offset:31232
	s_waitcnt lgkmcnt(14)
	v_mfma_f32_32x32x16_bf16 v[64:79], v[176:179], v[132:135], v[64:79]
	v_add_f32_e32 v2, v102, v2
	v_add_f32_e32 v2, v103, v2
	v_add_f32_e32 v2, v104, v2
	v_add_f32_e32 v2, v105, v2
	v_cvt_pk_bf16_f32 v146, v100, v101
	v_cvt_pk_bf16_f32 v147, v102, v103
	ds_read_b64_tr_b16 v[6:7], v4 offset:27648
	ds_read_b64_tr_b16 v[8:9], v4 offset:28160
	s_waitcnt lgkmcnt(14)
	v_mfma_f32_32x32x16_bf16 v[80:95], v[180:183], v[128:131], v[80:95]
	v_add_f32_e32 v2, v106, v2
	v_add_f32_e32 v2, v107, v2
	v_add_f32_e32 v2, v108, v2
	v_add_f32_e32 v15, v109, v2
	v_cvt_pk_bf16_f32 v136, v104, v105
	v_cvt_pk_bf16_f32 v137, v106, v107
	ds_read_b64_tr_b16 v[2:3], v4 offset:31744
	ds_read_b64_tr_b16 v[4:5], v4 offset:32256
	v_mfma_f32_32x32x16_bf16 v[64:79], v[172:175], v[128:131], v[64:79]
	v_add_f32_e32 v15, v110, v15
	v_add_f32_e32 v15, v111, v15
	v_cvt_pk_bf16_f32 v138, v108, v109
	v_cvt_pk_bf16_f32 v139, v110, v111
	v_max3_f32 v96, v80, v81, v82
	v_max3_f32 v97, v83, v84, v85
	v_max3_f32 v96, v96, v86, v87
	v_max3_f32 v97, v97, v88, v89
	v_max3_f32 v96, v96, v90, v91
	v_max3_f32 v97, v97, v92, v93
	v_max3_f32 v96, v96, v94, v95
	v_add_f32_e32 v223, v14, v15
	s_nop 0
	v_max3_f32 v97, v97, v64, v65
	v_max3_f32 v96, v96, v66, v67
	v_max3_f32 v97, v97, v68, v69
	v_max3_f32 v96, v96, v70, v71
	v_max3_f32 v97, v97, v72, v73
	v_max3_f32 v96, v96, v74, v75
	v_max3_f32 v97, v97, v76, v77
	v_max3_f32 v96, v96, v78, v79
	v_max_f32_e32 v14, v96, v97
	v_mov_b32_e32 v15, v14
	s_nop 1
	v_permlane32_swap_b32_e32 v14, v15
	s_add_i32 s8, s38, s46
	s_mov_b32 s9, m0
	s_mov_b32 m0, s8
	s_nop 0
	global_load_lds_dwordx4 v224, s[88:89]
	s_mov_b32 m0, s9
	v_max_f32_e32 v14, v14, v15
	s_add_i32 s8, s13, s47
	s_mov_b32 s9, m0
	s_mov_b32 m0, s8
	s_nop 0
	global_load_lds_dwordx4 v225, s[90:91]
	s_mov_b32 m0, s9
	v_cmp_lt_f32_e32 vcc, s53, v14
	s_cmp_lg_u64 vcc, 0
	s_cselect_b64 s[8:9], -1, 0
	s_cbranch_vccnz .LBB0_1558
; #define WAIT_BAR(N) asm volatile("s_waitcnt vmcnt(" #N ") lgkmcnt(0)\n\ts_barrier":::"memory")
;   #define RESC() do{ if(resc){ asm volatile("s_waitcnt lgkmcnt(0)":::"memory"); \
;       _Pragma("unroll") for(int d_=0;d_<2;++d_) _Pragma("unroll") for(int r=0;r<16;++r)o[d_][r]*=wsf[crow(r,hi)]; } }while(0)
;   #define ROT() do{sl_prev=sl_cur;sl_cur=sl_next;sl_next=(sl_next==(NSLOT-1)*SLOTB)?0:sl_next+SLOTB;}while(0)
; template<int THRL> __device__ __forceinline__ void attn_unit(int b,int h,int qb,const bf16*Q,const bf16*__restrict__ K,const bf16*__restrict__ V,bf16*O,char*shm,const int wid){
;     ...
;   int t=1;
;     ...
;   for(;t+5<NT;t+=2){
;     STEP(pB0,pB1,pA0,pA1,t,true,true,true);     WAIT_BAR(2); RESC(); ROT();
;     STEP(pA0,pA1,pB0,pB1,t+1,true,true,true);   WAIT_BAR(2); RESC(); ROT();
.LBB0_1551:
	s_waitcnt lgkmcnt(14)
	v_mfma_f32_32x32x16_bf16 v[32:47], v[156:159], v[168:171], v[32:47]
	v_exp_f32_e32 v80, v80
	v_exp_f32_e32 v81, v81
	v_exp_f32_e32 v82, v82
	v_exp_f32_e32 v83, v83
	s_waitcnt lgkmcnt(12)
	v_mfma_f32_32x32x16_bf16 v[16:31], v[156:159], v[164:167], v[16:31]
	v_exp_f32_e32 v84, v84
	v_exp_f32_e32 v85, v85
	v_exp_f32_e32 v86, v86
	v_exp_f32_e32 v87, v87
	v_add_u32_e32 v14, s13, v220
	ds_read_b128 v[188:191], v14
	ds_read_b128 v[184:187], v14 offset:512
	s_waitcnt lgkmcnt(12)
	v_mfma_f32_32x32x16_bf16 v[32:47], v[152:155], v[160:163], v[32:47]
	v_exp_f32_e32 v88, v88
	v_exp_f32_e32 v89, v89
	v_exp_f32_e32 v90, v90
	v_exp_f32_e32 v91, v91
	ds_read_b128 v[180:183], v14 offset:2048
	ds_read_b128 v[176:179], v14 offset:2560
	s_waitcnt lgkmcnt(12)
	v_mfma_f32_32x32x16_bf16 v[16:31], v[152:155], v[116:119], v[16:31]
	v_exp_f32_e32 v92, v92
	v_exp_f32_e32 v93, v93
	v_exp_f32_e32 v94, v94
	v_exp_f32_e32 v95, v95
	ds_read_b128 v[172:175], v14 offset:4096
	ds_read_b128 v[168:171], v14 offset:4608
	s_waitcnt lgkmcnt(12)
	v_mfma_f32_32x32x16_bf16 v[32:47], v[144:147], v[112:115], v[32:47]
	v_exp_f32_e32 v64, v64
	v_exp_f32_e32 v65, v65
	v_exp_f32_e32 v66, v66
	v_exp_f32_e32 v67, v67
	ds_read_b128 v[164:167], v14 offset:6144
	ds_read_b128 v[160:163], v14 offset:6656
	s_waitcnt lgkmcnt(12)
	v_mfma_f32_32x32x16_bf16 v[16:31], v[144:147], v[10:13], v[16:31]
	v_exp_f32_e32 v68, v68
	v_exp_f32_e32 v69, v69
	v_exp_f32_e32 v70, v70
	v_exp_f32_e32 v71, v71
	s_waitcnt lgkmcnt(10)
	v_mfma_f32_32x32x16_bf16 v[32:47], v[136:139], v[6:9], v[32:47]
	v_exp_f32_e32 v72, v72
	v_exp_f32_e32 v73, v73
	v_exp_f32_e32 v74, v74
	v_exp_f32_e32 v75, v75
	s_waitcnt lgkmcnt(8)
	v_mfma_f32_32x32x16_bf16 v[16:31], v[136:139], v[2:5], v[16:31]
	v_exp_f32_e32 v76, v76
	v_exp_f32_e32 v77, v77
	v_exp_f32_e32 v78, v78
	v_exp_f32_e32 v79, v79
	s_waitcnt vmcnt(2) lgkmcnt(0)
	s_barrier
	s_andn2_b64 vcc, exec, s[8:9]
	s_cbranch_vccnz .LBB0_1553
	s_waitcnt lgkmcnt(0)
	ds_read_b128 v[2:5], v226 offset:49248
	ds_read_b128 v[6:9], v226 offset:49216
	ds_read_b128 v[10:13], v226 offset:49184
	ds_read_b128 v[96:99], v226 offset:49152
	s_waitcnt lgkmcnt(3)
	v_pk_mul_f32 v[44:45], v[44:45], v[2:3]
	s_waitcnt lgkmcnt(2)
	v_pk_mul_f32 v[40:41], v[40:41], v[6:7]
	s_waitcnt lgkmcnt(1)
	v_pk_mul_f32 v[36:37], v[36:37], v[10:11]
	v_pk_mul_f32 v[46:47], v[46:47], v[4:5]
	v_pk_mul_f32 v[42:43], v[42:43], v[8:9]
	v_pk_mul_f32 v[38:39], v[38:39], v[12:13]
	s_waitcnt lgkmcnt(0)
	v_pk_mul_f32 v[34:35], v[34:35], v[98:99]
	v_pk_mul_f32 v[32:33], v[32:33], v[96:97]
	v_pk_mul_f32 v[28:29], v[28:29], v[2:3]
	v_pk_mul_f32 v[24:25], v[24:25], v[6:7]
	v_pk_mul_f32 v[20:21], v[20:21], v[10:11]
	v_pk_mul_f32 v[30:31], v[30:31], v[4:5]
	v_pk_mul_f32 v[26:27], v[26:27], v[8:9]
	v_pk_mul_f32 v[22:23], v[22:23], v[12:13]
	v_pk_mul_f32 v[18:19], v[18:19], v[98:99]
	v_pk_mul_f32 v[16:17], v[16:17], v[96:97]
.LBB0_1553:
	s_add_i32 s8, s13, 0x2000
	s_cmpk_lg_i32 s13, 0x4000
	s_cselect_b32 s55, s8, 0
	s_add_u32 s90, s90, s28
	s_addc_u32 s91, s91, s29
	s_add_u32 s88, s88, s28
	s_addc_u32 s89, s89, s29
	s_add_i32 s8, s39, 2
	s_cmp_ge_u32 s8, s3
	s_cbranch_scc1 .LBB0_1568
	s_mov_b32 s39, s8
	s_mov_b32 s8, s38
	s_mov_b32 s40, s13
	s_mov_b32 s38, s55
	s_branch .LBB0_1547
